# GEMM bf16 main loops: additional s_setprio 0/1 flip after every 8 MFMAs (24 flips), on the v34 configuration
# baseline (speedup 1.0000x reference)
.LBB0_248:
	s_add_u32 s81, s14, s40
	s_addc_u32 s83, s15, s41
	s_add_u32 s42, s81, 0x100
	s_addc_u32 s43, s83, 0
	s_add_u32 s44, s22, s40
	s_addc_u32 s45, s23, s41
	s_add_u32 s44, s44, 0x100
	s_addc_u32 s45, s45, 0
	s_cmp_eq_u32 s80, 60
	s_cselect_b32 s46, s13, s42
	s_cselect_b32 s47, s9, s43
	s_cselect_b32 s44, s35, s44
	s_cselect_b32 s45, s17, s45
	s_add_u32 s42, s46, 0x80
	s_addc_u32 s43, s47, 0
	s_add_i32 s84, 0, 0x10000
	v_add_u32_e32 v0, s84, v153
	s_add_i32 s85, 0, 0x14000
	ds_read_b128 v[92:95], v0
	ds_read_b128 v[96:99], v0 offset:1024
	ds_read_b128 v[100:103], v0 offset:2048
	ds_read_b128 v[104:107], v0 offset:3072
	v_add_u32_e32 v0, s85, v153
	ds_read_b128 v[156:159], v0
	ds_read_b128 v[160:163], v0 offset:1024
	ds_read_b128 v[164:167], v0 offset:2048
	ds_read_b128 v[168:171], v0 offset:3072
	s_add_u32 s82, s81, 0x100080
	s_addc_u32 s83, s83, 0
	v_mov_b32_e32 v0, v2
	ds_read_b128 v[172:175], v154
	ds_read_b128 v[176:179], v154 offset:1024
	ds_read_b128 v[180:183], v154 offset:2048
	ds_read_b128 v[198:201], v154 offset:3072
	ds_read_b128 v[202:205], v154 offset:4096
	ds_read_b128 v[206:209], v154 offset:5120
	ds_read_b128 v[210:213], v154 offset:6144
	ds_read_b128 v[214:217], v154 offset:7168
	s_add_i32 m0, s58, 0xc000
	s_nop 0
	global_load_lds_dwordx4 v0, s[82:83]
	v_mov_b32_e32 v0, v151
	s_add_i32 m0, s58, 0xe000
	s_nop 0
	global_load_lds_dwordx4 v0, s[82:83]
	s_waitcnt vmcnt(8)
	s_waitcnt lgkmcnt(0)
	s_barrier
	s_setprio 1
	s_waitcnt lgkmcnt(0)
	v_mfma_f32_16x16x32_bf16 v[144:147], v[92:95], v[172:175], v[144:147]
	v_mfma_f32_16x16x32_bf16 v[140:143], v[100:103], v[172:175], v[140:143]
	v_mfma_f32_16x16x32_bf16 v[128:131], v[92:95], v[180:183], v[128:131]
	v_mfma_f32_16x16x32_bf16 v[124:127], v[100:103], v[180:183], v[124:127]
	v_mfma_f32_16x16x32_bf16 v[112:115], v[92:95], v[202:205], v[112:115]
	v_mfma_f32_16x16x32_bf16 v[108:111], v[100:103], v[202:205], v[108:111]
	v_mfma_f32_16x16x32_bf16 v[80:83], v[92:95], v[210:213], v[80:83]
	v_mfma_f32_16x16x32_bf16 v[76:79], v[100:103], v[210:213], v[76:79]
	s_setprio 0
	s_setprio 1
	v_mfma_f32_16x16x32_bf16 v[144:147], v[96:99], v[176:179], v[144:147]
	v_mfma_f32_16x16x32_bf16 v[140:143], v[104:107], v[176:179], v[140:143]
	v_mfma_f32_16x16x32_bf16 v[128:131], v[96:99], v[198:201], v[128:131]
	v_mfma_f32_16x16x32_bf16 v[124:127], v[104:107], v[198:201], v[124:127]
	v_mfma_f32_16x16x32_bf16 v[112:115], v[96:99], v[206:209], v[112:115]
	v_mfma_f32_16x16x32_bf16 v[108:111], v[104:107], v[206:209], v[108:111]
	v_mfma_f32_16x16x32_bf16 v[80:83], v[96:99], v[214:217], v[80:83]
	v_mfma_f32_16x16x32_bf16 v[76:79], v[104:107], v[214:217], v[76:79]
	s_setprio 0
	s_setprio 1
	v_mfma_f32_16x16x32_bf16 v[136:139], v[156:159], v[172:175], v[136:139]
	v_mfma_f32_16x16x32_bf16 v[132:135], v[164:167], v[172:175], v[132:135]
	v_mfma_f32_16x16x32_bf16 v[120:123], v[156:159], v[180:183], v[120:123]
	v_mfma_f32_16x16x32_bf16 v[116:119], v[164:167], v[180:183], v[116:119]
	v_mfma_f32_16x16x32_bf16 v[88:91], v[156:159], v[202:205], v[88:91]
	v_mfma_f32_16x16x32_bf16 v[84:87], v[164:167], v[202:205], v[84:87]
	v_mfma_f32_16x16x32_bf16 v[72:75], v[156:159], v[210:213], v[72:75]
	v_mfma_f32_16x16x32_bf16 v[68:71], v[164:167], v[210:213], v[68:71]
	s_setprio 0
	s_setprio 1
	v_mfma_f32_16x16x32_bf16 v[136:139], v[160:163], v[176:179], v[136:139]
	v_mfma_f32_16x16x32_bf16 v[132:135], v[168:171], v[176:179], v[132:135]
	v_mfma_f32_16x16x32_bf16 v[120:123], v[160:163], v[198:201], v[120:123]
	v_mfma_f32_16x16x32_bf16 v[116:119], v[168:171], v[198:201], v[116:119]
	v_mfma_f32_16x16x32_bf16 v[88:91], v[160:163], v[206:209], v[88:91]
	v_mfma_f32_16x16x32_bf16 v[84:87], v[168:171], v[206:209], v[84:87]
	v_mfma_f32_16x16x32_bf16 v[72:75], v[160:163], v[214:217], v[72:75]
	v_mfma_f32_16x16x32_bf16 v[68:71], v[168:171], v[214:217], v[68:71]
	s_setprio 0
	s_barrier
	s_mov_b64 s[82:83], s[44:45]
	v_mov_b32_e32 v0, v150
	s_add_i32 s81, s84, s57
	ds_read_b128 v[172:175], v154 offset:16384
	ds_read_b128 v[176:179], v154 offset:17408
	ds_read_b128 v[180:183], v154 offset:18432
	ds_read_b128 v[198:201], v154 offset:19456
	ds_read_b128 v[202:205], v154 offset:20480
	ds_read_b128 v[206:209], v154 offset:21504
	ds_read_b128 v[210:213], v154 offset:22528
	ds_read_b128 v[214:217], v154 offset:23552
	s_mov_b32 m0, s81
	s_nop 0
	global_load_lds_dwordx4 v0, s[82:83]
	v_mov_b32_e32 v0, v152
	s_add_i32 m0, s81, 0x2000
	s_nop 0
	global_load_lds_dwordx4 v0, s[82:83]
	s_add_u32 s82, s44, 0x100000
	s_addc_u32 s83, s45, 0
	v_mov_b32_e32 v0, v150
	s_add_i32 s81, s85, s57
	s_mov_b32 m0, s81
	s_nop 0
	global_load_lds_dwordx4 v0, s[82:83]
	v_mov_b32_e32 v0, v152
	s_add_i32 m0, s81, 0x2000
	s_nop 0
	global_load_lds_dwordx4 v0, s[82:83]
	s_mov_b64 s[82:83], s[46:47]
	v_mov_b32_e32 v0, v2
	s_mov_b32 m0, s58
	s_nop 0
	global_load_lds_dwordx4 v0, s[82:83]
	v_mov_b32_e32 v0, v151
	s_mov_b32 m0, s60
	s_nop 0
	global_load_lds_dwordx4 v0, s[82:83]
	s_waitcnt vmcnt(8)
	s_waitcnt lgkmcnt(0)
	s_barrier
	s_setprio 1
	s_waitcnt lgkmcnt(0)
	v_mfma_f32_16x16x32_bf16 v[64:67], v[92:95], v[172:175], v[64:67]
	v_mfma_f32_16x16x32_bf16 v[60:63], v[100:103], v[172:175], v[60:63]
	v_mfma_f32_16x16x32_bf16 v[48:51], v[92:95], v[180:183], v[48:51]
	v_mfma_f32_16x16x32_bf16 v[44:47], v[100:103], v[180:183], v[44:47]
	v_mfma_f32_16x16x32_bf16 v[32:35], v[92:95], v[202:205], v[32:35]
	v_mfma_f32_16x16x32_bf16 v[28:31], v[100:103], v[202:205], v[28:31]
	v_mfma_f32_16x16x32_bf16 v[16:19], v[92:95], v[210:213], v[16:19]
	v_mfma_f32_16x16x32_bf16 v[12:15], v[100:103], v[210:213], v[12:15]
	s_setprio 0
	s_setprio 1
	v_mfma_f32_16x16x32_bf16 v[64:67], v[96:99], v[176:179], v[64:67]
	v_mfma_f32_16x16x32_bf16 v[60:63], v[104:107], v[176:179], v[60:63]
	v_mfma_f32_16x16x32_bf16 v[48:51], v[96:99], v[198:201], v[48:51]
	v_mfma_f32_16x16x32_bf16 v[44:47], v[104:107], v[198:201], v[44:47]
	v_mfma_f32_16x16x32_bf16 v[32:35], v[96:99], v[206:209], v[32:35]
	v_mfma_f32_16x16x32_bf16 v[28:31], v[104:107], v[206:209], v[28:31]
	v_mfma_f32_16x16x32_bf16 v[16:19], v[96:99], v[214:217], v[16:19]
	v_mfma_f32_16x16x32_bf16 v[12:15], v[104:107], v[214:217], v[12:15]
	s_setprio 0
	s_setprio 1
	v_mfma_f32_16x16x32_bf16 v[56:59], v[156:159], v[172:175], v[56:59]
	v_mfma_f32_16x16x32_bf16 v[52:55], v[164:167], v[172:175], v[52:55]
	v_mfma_f32_16x16x32_bf16 v[40:43], v[156:159], v[180:183], v[40:43]
	v_mfma_f32_16x16x32_bf16 v[36:39], v[164:167], v[180:183], v[36:39]
	v_mfma_f32_16x16x32_bf16 v[24:27], v[156:159], v[202:205], v[24:27]
	v_mfma_f32_16x16x32_bf16 v[20:23], v[164:167], v[202:205], v[20:23]
	v_mfma_f32_16x16x32_bf16 v[8:11], v[156:159], v[210:213], v[8:11]
	v_mfma_f32_16x16x32_bf16 v[4:7], v[164:167], v[210:213], v[4:7]
	s_setprio 0
	s_setprio 1
	v_mfma_f32_16x16x32_bf16 v[56:59], v[160:163], v[176:179], v[56:59]
	v_mfma_f32_16x16x32_bf16 v[52:55], v[168:171], v[176:179], v[52:55]
	v_mfma_f32_16x16x32_bf16 v[40:43], v[160:163], v[198:201], v[40:43]
	v_mfma_f32_16x16x32_bf16 v[36:39], v[168:171], v[198:201], v[36:39]
	v_mfma_f32_16x16x32_bf16 v[24:27], v[160:163], v[206:209], v[24:27]
	v_mfma_f32_16x16x32_bf16 v[20:23], v[168:171], v[206:209], v[20:23]
	v_mfma_f32_16x16x32_bf16 v[8:11], v[160:163], v[214:217], v[8:11]
	v_mfma_f32_16x16x32_bf16 v[4:7], v[168:171], v[214:217], v[4:7]
	s_setprio 0
	s_barrier
	s_add_i32 s81, 0, 0x18000
	v_add_u32_e32 v0, s81, v153
	s_add_i32 s82, 0, 0x1c000
	ds_read_b128 v[92:95], v0
	ds_read_b128 v[96:99], v0 offset:1024
	ds_read_b128 v[100:103], v0 offset:2048
	ds_read_b128 v[104:107], v0 offset:3072
	v_add_u32_e32 v0, s82, v153
	ds_read_b128 v[156:159], v0
	ds_read_b128 v[160:163], v0 offset:1024
	ds_read_b128 v[164:167], v0 offset:2048
	ds_read_b128 v[168:171], v0 offset:3072
	s_add_u32 s46, s46, 0x100000
	s_addc_u32 s47, s47, 0
	v_mov_b32_e32 v0, v2
	s_mov_b32 m0, s61
	ds_read_b128 v[172:175], v154 offset:32768
	ds_read_b128 v[176:179], v154 offset:33792
	ds_read_b128 v[180:183], v154 offset:34816
	ds_read_b128 v[198:201], v154 offset:35840
	ds_read_b128 v[202:205], v154 offset:36864
	ds_read_b128 v[206:209], v154 offset:37888
	ds_read_b128 v[210:213], v154 offset:38912
	ds_read_b128 v[214:217], v154 offset:39936
	s_nop 0
	global_load_lds_dwordx4 v0, s[46:47]
	v_mov_b32_e32 v0, v151
	s_mov_b32 m0, s62
	s_nop 0
	global_load_lds_dwordx4 v0, s[46:47]
	s_waitcnt vmcnt(8)
	s_waitcnt lgkmcnt(0)
	s_barrier
	s_setprio 1
	s_waitcnt lgkmcnt(0)
	v_mfma_f32_16x16x32_bf16 v[144:147], v[92:95], v[172:175], v[144:147]
	v_mfma_f32_16x16x32_bf16 v[140:143], v[100:103], v[172:175], v[140:143]
	v_mfma_f32_16x16x32_bf16 v[128:131], v[92:95], v[180:183], v[128:131]
	v_mfma_f32_16x16x32_bf16 v[124:127], v[100:103], v[180:183], v[124:127]
	v_mfma_f32_16x16x32_bf16 v[112:115], v[92:95], v[202:205], v[112:115]
	v_mfma_f32_16x16x32_bf16 v[108:111], v[100:103], v[202:205], v[108:111]
	v_mfma_f32_16x16x32_bf16 v[80:83], v[92:95], v[210:213], v[80:83]
	v_mfma_f32_16x16x32_bf16 v[76:79], v[100:103], v[210:213], v[76:79]
	s_setprio 0
	s_setprio 1
	v_mfma_f32_16x16x32_bf16 v[144:147], v[96:99], v[176:179], v[144:147]
	v_mfma_f32_16x16x32_bf16 v[140:143], v[104:107], v[176:179], v[140:143]
	v_mfma_f32_16x16x32_bf16 v[128:131], v[96:99], v[198:201], v[128:131]
	v_mfma_f32_16x16x32_bf16 v[124:127], v[104:107], v[198:201], v[124:127]
	v_mfma_f32_16x16x32_bf16 v[112:115], v[96:99], v[206:209], v[112:115]
	v_mfma_f32_16x16x32_bf16 v[108:111], v[104:107], v[206:209], v[108:111]
	v_mfma_f32_16x16x32_bf16 v[80:83], v[96:99], v[214:217], v[80:83]
	v_mfma_f32_16x16x32_bf16 v[76:79], v[104:107], v[214:217], v[76:79]
	s_setprio 0
	s_setprio 1
	v_mfma_f32_16x16x32_bf16 v[136:139], v[156:159], v[172:175], v[136:139]
	v_mfma_f32_16x16x32_bf16 v[132:135], v[164:167], v[172:175], v[132:135]
	v_mfma_f32_16x16x32_bf16 v[120:123], v[156:159], v[180:183], v[120:123]
	v_mfma_f32_16x16x32_bf16 v[116:119], v[164:167], v[180:183], v[116:119]
	v_mfma_f32_16x16x32_bf16 v[88:91], v[156:159], v[202:205], v[88:91]
	v_mfma_f32_16x16x32_bf16 v[84:87], v[164:167], v[202:205], v[84:87]
	v_mfma_f32_16x16x32_bf16 v[72:75], v[156:159], v[210:213], v[72:75]
	v_mfma_f32_16x16x32_bf16 v[68:71], v[164:167], v[210:213], v[68:71]
	s_setprio 0
	s_setprio 1
	v_mfma_f32_16x16x32_bf16 v[136:139], v[160:163], v[176:179], v[136:139]
	v_mfma_f32_16x16x32_bf16 v[132:135], v[168:171], v[176:179], v[132:135]
	v_mfma_f32_16x16x32_bf16 v[120:123], v[160:163], v[198:201], v[120:123]
	v_mfma_f32_16x16x32_bf16 v[116:119], v[168:171], v[198:201], v[116:119]
	v_mfma_f32_16x16x32_bf16 v[88:91], v[160:163], v[206:209], v[88:91]
	v_mfma_f32_16x16x32_bf16 v[84:87], v[168:171], v[206:209], v[84:87]
	v_mfma_f32_16x16x32_bf16 v[72:75], v[160:163], v[214:217], v[72:75]
	v_mfma_f32_16x16x32_bf16 v[68:71], v[168:171], v[214:217], v[68:71]
	s_setprio 0
	s_barrier
	s_add_u32 s46, s44, 0x80
	s_addc_u32 s47, s45, 0
	v_mov_b32_e32 v0, v150
	s_add_i32 s81, s81, s57
	ds_read_b128 v[172:175], v154 offset:49152
	ds_read_b128 v[176:179], v154 offset:50176
	ds_read_b128 v[180:183], v154 offset:51200
	ds_read_b128 v[198:201], v154 offset:52224
	ds_read_b128 v[202:205], v154 offset:53248
	ds_read_b128 v[206:209], v154 offset:54272
	ds_read_b128 v[210:213], v154 offset:55296
	ds_read_b128 v[214:217], v154 offset:56320
	s_mov_b32 m0, s81
	s_nop 0
	global_load_lds_dwordx4 v0, s[46:47]
	v_mov_b32_e32 v0, v152
	s_add_i32 m0, s81, 0x2000
	s_add_u32 s44, s44, 0x100080
	global_load_lds_dwordx4 v0, s[46:47]
	s_addc_u32 s45, s45, 0
	v_mov_b32_e32 v0, v150
	s_add_i32 s46, s82, s57
	s_mov_b32 m0, s46
	s_nop 0
	global_load_lds_dwordx4 v0, s[44:45]
	v_mov_b32_e32 v0, v152
	s_add_i32 m0, s46, 0x2000
	s_nop 0
	global_load_lds_dwordx4 v0, s[44:45]
	v_mov_b32_e32 v0, v2
	s_mov_b32 m0, s96
	s_nop 0
	global_load_lds_dwordx4 v0, s[42:43]
	v_mov_b32_e32 v0, v151
	s_mov_b32 m0, s97
	s_nop 0
	global_load_lds_dwordx4 v0, s[42:43]
	s_waitcnt vmcnt(8)
	s_waitcnt lgkmcnt(0)
	s_barrier
	s_setprio 1
	s_waitcnt lgkmcnt(0)
	v_mfma_f32_16x16x32_bf16 v[64:67], v[92:95], v[172:175], v[64:67]
	v_mfma_f32_16x16x32_bf16 v[60:63], v[100:103], v[172:175], v[60:63]
	v_mfma_f32_16x16x32_bf16 v[48:51], v[92:95], v[180:183], v[48:51]
	v_mfma_f32_16x16x32_bf16 v[44:47], v[100:103], v[180:183], v[44:47]
	v_mfma_f32_16x16x32_bf16 v[32:35], v[92:95], v[202:205], v[32:35]
	v_mfma_f32_16x16x32_bf16 v[28:31], v[100:103], v[202:205], v[28:31]
	v_mfma_f32_16x16x32_bf16 v[16:19], v[92:95], v[210:213], v[16:19]
	v_mfma_f32_16x16x32_bf16 v[12:15], v[100:103], v[210:213], v[12:15]
	s_setprio 0
	s_setprio 1
	v_mfma_f32_16x16x32_bf16 v[64:67], v[96:99], v[176:179], v[64:67]
	v_mfma_f32_16x16x32_bf16 v[60:63], v[104:107], v[176:179], v[60:63]
	v_mfma_f32_16x16x32_bf16 v[48:51], v[96:99], v[198:201], v[48:51]
	v_mfma_f32_16x16x32_bf16 v[44:47], v[104:107], v[198:201], v[44:47]
	v_mfma_f32_16x16x32_bf16 v[32:35], v[96:99], v[206:209], v[32:35]
	v_mfma_f32_16x16x32_bf16 v[28:31], v[104:107], v[206:209], v[28:31]
	v_mfma_f32_16x16x32_bf16 v[16:19], v[96:99], v[214:217], v[16:19]
	v_mfma_f32_16x16x32_bf16 v[12:15], v[104:107], v[214:217], v[12:15]
	s_setprio 0
	s_setprio 1
	v_mfma_f32_16x16x32_bf16 v[56:59], v[156:159], v[172:175], v[56:59]
	v_mfma_f32_16x16x32_bf16 v[52:55], v[164:167], v[172:175], v[52:55]
	v_mfma_f32_16x16x32_bf16 v[40:43], v[156:159], v[180:183], v[40:43]
	v_mfma_f32_16x16x32_bf16 v[36:39], v[164:167], v[180:183], v[36:39]
	v_mfma_f32_16x16x32_bf16 v[24:27], v[156:159], v[202:205], v[24:27]
	v_mfma_f32_16x16x32_bf16 v[20:23], v[164:167], v[202:205], v[20:23]
	v_mfma_f32_16x16x32_bf16 v[8:11], v[156:159], v[210:213], v[8:11]
	v_mfma_f32_16x16x32_bf16 v[4:7], v[164:167], v[210:213], v[4:7]
	s_setprio 0
	s_setprio 1
	v_mfma_f32_16x16x32_bf16 v[56:59], v[160:163], v[176:179], v[56:59]
	v_mfma_f32_16x16x32_bf16 v[52:55], v[168:171], v[176:179], v[52:55]
	v_mfma_f32_16x16x32_bf16 v[40:43], v[160:163], v[198:201], v[40:43]
	v_mfma_f32_16x16x32_bf16 v[36:39], v[168:171], v[198:201], v[36:39]
	v_mfma_f32_16x16x32_bf16 v[24:27], v[160:163], v[206:209], v[24:27]
	v_mfma_f32_16x16x32_bf16 v[20:23], v[168:171], v[206:209], v[20:23]
	v_mfma_f32_16x16x32_bf16 v[8:11], v[160:163], v[214:217], v[8:11]
	v_mfma_f32_16x16x32_bf16 v[4:7], v[168:171], v[214:217], v[4:7]
	s_setprio 0
	s_barrier
	s_add_i32 s80, s80, 2
	s_add_u32 s40, s40, 0x100
	s_addc_u32 s41, s41, 0
	s_cmp_gt_u32 s80, 61
	s_cbranch_scc0 .LBB0_248
	s_and_b64 vcc, exec, s[4:5]
	s_cbranch_vccz .LBB0_251
	s_barrier

.LBB0_1827:
	s_add_i32 s13, s49, 2
	s_add_u32 s51, s20, s22
	s_addc_u32 s62, s21, s23
	s_add_u32 s58, s51, 0x100
	s_addc_u32 s59, s62, 0
	s_add_u32 s60, s14, s22
	s_addc_u32 s61, s15, s23
	s_add_u32 s60, s60, 0x100
	s_addc_u32 s61, s61, 0
	s_cmp_eq_u32 s3, s49
	s_cselect_b32 s96, s52, s58
	s_cselect_b32 s97, s53, s59
	s_cselect_b32 s60, s54, s60
	s_cselect_b32 s61, s55, s61
	s_add_u32 s58, s96, 0x80
	s_addc_u32 s59, s97, 0
	s_add_i32 s49, 0, 0x10000
	v_add_u32_e32 v0, s49, v160
	s_add_i32 s82, 0, 0x14000
	ds_read_b128 v[132:135], v0
	ds_read_b128 v[136:139], v0 offset:1024
	ds_read_b128 v[140:143], v0 offset:2048
	ds_read_b128 v[144:147], v0 offset:3072
	v_add_u32_e32 v0, s82, v160
	ds_read_b128 v[148:151], v0
	ds_read_b128 v[152:155], v0 offset:1024
	ds_read_b128 v[162:165], v0 offset:2048
	ds_read_b128 v[166:169], v0 offset:3072
	s_add_u32 s80, s51, 0x80080
	s_addc_u32 s81, s62, 0
	v_mov_b32_e32 v0, v156
	ds_read_b128 v[170:173], v161
	ds_read_b128 v[174:177], v161 offset:1024
	ds_read_b128 v[178:181], v161 offset:2048
	ds_read_b128 v[182:185], v161 offset:3072
	ds_read_b128 v[186:189], v161 offset:4096
	ds_read_b128 v[190:193], v161 offset:5120
	ds_read_b128 v[194:197], v161 offset:6144
	ds_read_b128 v[198:201], v161 offset:7168
	s_add_i32 m0, s19, 0xc000
	s_nop 0
	global_load_lds_dwordx4 v0, s[80:81]
	v_mov_b32_e32 v0, v158
	s_add_i32 m0, s19, 0xe000
	s_nop 0
	global_load_lds_dwordx4 v0, s[80:81]
	s_waitcnt vmcnt(8)
	s_waitcnt lgkmcnt(0)
	s_barrier
	s_setprio 1
	s_waitcnt lgkmcnt(0)
	v_mfma_f32_16x16x32_bf16 v[128:131], v[132:135], v[170:173], v[128:131]
	v_mfma_f32_16x16x32_bf16 v[124:127], v[140:143], v[170:173], v[124:127]
	v_mfma_f32_16x16x32_bf16 v[112:115], v[132:135], v[178:181], v[112:115]
	v_mfma_f32_16x16x32_bf16 v[108:111], v[140:143], v[178:181], v[108:111]
	v_mfma_f32_16x16x32_bf16 v[96:99], v[132:135], v[186:189], v[96:99]
	v_mfma_f32_16x16x32_bf16 v[92:95], v[140:143], v[186:189], v[92:95]
	v_mfma_f32_16x16x32_bf16 v[80:83], v[132:135], v[194:197], v[80:83]
	v_mfma_f32_16x16x32_bf16 v[76:79], v[140:143], v[194:197], v[76:79]
	s_setprio 0
	s_setprio 1
	v_mfma_f32_16x16x32_bf16 v[128:131], v[136:139], v[174:177], v[128:131]
	v_mfma_f32_16x16x32_bf16 v[124:127], v[144:147], v[174:177], v[124:127]
	v_mfma_f32_16x16x32_bf16 v[112:115], v[136:139], v[182:185], v[112:115]
	v_mfma_f32_16x16x32_bf16 v[108:111], v[144:147], v[182:185], v[108:111]
	v_mfma_f32_16x16x32_bf16 v[96:99], v[136:139], v[190:193], v[96:99]
	v_mfma_f32_16x16x32_bf16 v[92:95], v[144:147], v[190:193], v[92:95]
	v_mfma_f32_16x16x32_bf16 v[80:83], v[136:139], v[198:201], v[80:83]
	v_mfma_f32_16x16x32_bf16 v[76:79], v[144:147], v[198:201], v[76:79]
	s_setprio 0
	s_setprio 1
	v_mfma_f32_16x16x32_bf16 v[120:123], v[148:151], v[170:173], v[120:123]
	v_mfma_f32_16x16x32_bf16 v[116:119], v[162:165], v[170:173], v[116:119]
	v_mfma_f32_16x16x32_bf16 v[104:107], v[148:151], v[178:181], v[104:107]
	v_mfma_f32_16x16x32_bf16 v[100:103], v[162:165], v[178:181], v[100:103]
	v_mfma_f32_16x16x32_bf16 v[88:91], v[148:151], v[186:189], v[88:91]
	v_mfma_f32_16x16x32_bf16 v[84:87], v[162:165], v[186:189], v[84:87]
	v_mfma_f32_16x16x32_bf16 v[72:75], v[148:151], v[194:197], v[72:75]
	v_mfma_f32_16x16x32_bf16 v[68:71], v[162:165], v[194:197], v[68:71]
	s_setprio 0
	s_setprio 1
	v_mfma_f32_16x16x32_bf16 v[120:123], v[152:155], v[174:177], v[120:123]
	v_mfma_f32_16x16x32_bf16 v[116:119], v[166:169], v[174:177], v[116:119]
	v_mfma_f32_16x16x32_bf16 v[104:107], v[152:155], v[182:185], v[104:107]
	v_mfma_f32_16x16x32_bf16 v[100:103], v[166:169], v[182:185], v[100:103]
	v_mfma_f32_16x16x32_bf16 v[88:91], v[152:155], v[190:193], v[88:91]
	v_mfma_f32_16x16x32_bf16 v[84:87], v[166:169], v[190:193], v[84:87]
	v_mfma_f32_16x16x32_bf16 v[72:75], v[152:155], v[198:201], v[72:75]
	v_mfma_f32_16x16x32_bf16 v[68:71], v[166:169], v[198:201], v[68:71]
	s_setprio 0
	s_barrier
	s_mov_b64 s[80:81], s[60:61]
	v_mov_b32_e32 v0, v157
	s_add_i32 s49, s49, s18
	ds_read_b128 v[170:173], v161 offset:16384
	ds_read_b128 v[174:177], v161 offset:17408
	ds_read_b128 v[178:181], v161 offset:18432
	ds_read_b128 v[182:185], v161 offset:19456
	ds_read_b128 v[186:189], v161 offset:20480
	ds_read_b128 v[190:193], v161 offset:21504
	ds_read_b128 v[194:197], v161 offset:22528
	ds_read_b128 v[198:201], v161 offset:23552
	s_mov_b32 m0, s49
	s_nop 0
	global_load_lds_dwordx4 v0, s[80:81]
	v_mov_b32_e32 v0, v159
	s_add_i32 m0, s49, 0x2000
	s_nop 0
	global_load_lds_dwordx4 v0, s[80:81]
	s_add_u32 s80, s60, 0x80000
	s_addc_u32 s81, s61, 0
	v_mov_b32_e32 v0, v157
	s_add_i32 s49, s82, s18
	s_mov_b32 m0, s49
	s_nop 0
	global_load_lds_dwordx4 v0, s[80:81]
	v_mov_b32_e32 v0, v159
	s_add_i32 m0, s49, 0x2000
	s_nop 0
	global_load_lds_dwordx4 v0, s[80:81]
	s_mov_b64 s[80:81], s[96:97]
	v_mov_b32_e32 v0, v156
	s_mov_b32 m0, s19
	s_nop 0
	global_load_lds_dwordx4 v0, s[80:81]
	v_mov_b32_e32 v0, v158
	s_mov_b32 m0, s38
	s_nop 0
	global_load_lds_dwordx4 v0, s[80:81]
	s_waitcnt vmcnt(8)
	s_waitcnt lgkmcnt(0)
	s_barrier
	s_setprio 1
	s_waitcnt lgkmcnt(0)
	v_mfma_f32_16x16x32_bf16 v[64:67], v[132:135], v[170:173], v[64:67]
	v_mfma_f32_16x16x32_bf16 v[60:63], v[140:143], v[170:173], v[60:63]
	v_mfma_f32_16x16x32_bf16 v[48:51], v[132:135], v[178:181], v[48:51]
	v_mfma_f32_16x16x32_bf16 v[44:47], v[140:143], v[178:181], v[44:47]
	v_mfma_f32_16x16x32_bf16 v[32:35], v[132:135], v[186:189], v[32:35]
	v_mfma_f32_16x16x32_bf16 v[28:31], v[140:143], v[186:189], v[28:31]
	v_mfma_f32_16x16x32_bf16 v[16:19], v[132:135], v[194:197], v[16:19]
	v_mfma_f32_16x16x32_bf16 v[12:15], v[140:143], v[194:197], v[12:15]
	s_setprio 0
	s_setprio 1
	v_mfma_f32_16x16x32_bf16 v[64:67], v[136:139], v[174:177], v[64:67]
	v_mfma_f32_16x16x32_bf16 v[60:63], v[144:147], v[174:177], v[60:63]
	v_mfma_f32_16x16x32_bf16 v[48:51], v[136:139], v[182:185], v[48:51]
	v_mfma_f32_16x16x32_bf16 v[44:47], v[144:147], v[182:185], v[44:47]
	v_mfma_f32_16x16x32_bf16 v[32:35], v[136:139], v[190:193], v[32:35]
	v_mfma_f32_16x16x32_bf16 v[28:31], v[144:147], v[190:193], v[28:31]
	v_mfma_f32_16x16x32_bf16 v[16:19], v[136:139], v[198:201], v[16:19]
	v_mfma_f32_16x16x32_bf16 v[12:15], v[144:147], v[198:201], v[12:15]
	s_setprio 0
	s_setprio 1
	v_mfma_f32_16x16x32_bf16 v[56:59], v[148:151], v[170:173], v[56:59]
	v_mfma_f32_16x16x32_bf16 v[52:55], v[162:165], v[170:173], v[52:55]
	v_mfma_f32_16x16x32_bf16 v[40:43], v[148:151], v[178:181], v[40:43]
	v_mfma_f32_16x16x32_bf16 v[36:39], v[162:165], v[178:181], v[36:39]
	v_mfma_f32_16x16x32_bf16 v[24:27], v[148:151], v[186:189], v[24:27]
	v_mfma_f32_16x16x32_bf16 v[20:23], v[162:165], v[186:189], v[20:23]
	v_mfma_f32_16x16x32_bf16 v[8:11], v[148:151], v[194:197], v[8:11]
	v_mfma_f32_16x16x32_bf16 v[4:7], v[162:165], v[194:197], v[4:7]
	s_setprio 0
	s_setprio 1
	v_mfma_f32_16x16x32_bf16 v[56:59], v[152:155], v[174:177], v[56:59]
	v_mfma_f32_16x16x32_bf16 v[52:55], v[166:169], v[174:177], v[52:55]
	v_mfma_f32_16x16x32_bf16 v[40:43], v[152:155], v[182:185], v[40:43]
	v_mfma_f32_16x16x32_bf16 v[36:39], v[166:169], v[182:185], v[36:39]
	v_mfma_f32_16x16x32_bf16 v[24:27], v[152:155], v[190:193], v[24:27]
	v_mfma_f32_16x16x32_bf16 v[20:23], v[166:169], v[190:193], v[20:23]
	v_mfma_f32_16x16x32_bf16 v[8:11], v[152:155], v[198:201], v[8:11]
	v_mfma_f32_16x16x32_bf16 v[4:7], v[166:169], v[198:201], v[4:7]
	s_setprio 0
	s_barrier
	s_add_i32 s49, 0, 0x18000
	v_add_u32_e32 v0, s49, v160
	s_add_i32 s51, 0, 0x1c000
	ds_read_b128 v[132:135], v0
	ds_read_b128 v[136:139], v0 offset:1024
	ds_read_b128 v[140:143], v0 offset:2048
	ds_read_b128 v[144:147], v0 offset:3072
	v_add_u32_e32 v0, s51, v160
	ds_read_b128 v[148:151], v0
	ds_read_b128 v[152:155], v0 offset:1024
	ds_read_b128 v[162:165], v0 offset:2048
	ds_read_b128 v[166:169], v0 offset:3072
	s_add_u32 s80, s96, 0x80000
	s_addc_u32 s81, s97, 0
	v_mov_b32_e32 v0, v156
	s_mov_b32 m0, s6
	ds_read_b128 v[170:173], v161 offset:32768
	ds_read_b128 v[174:177], v161 offset:33792
	ds_read_b128 v[178:181], v161 offset:34816
	ds_read_b128 v[182:185], v161 offset:35840
	ds_read_b128 v[186:189], v161 offset:36864
	ds_read_b128 v[190:193], v161 offset:37888
	ds_read_b128 v[194:197], v161 offset:38912
	ds_read_b128 v[198:201], v161 offset:39936
	s_nop 0
	global_load_lds_dwordx4 v0, s[80:81]
	v_mov_b32_e32 v0, v158
	s_mov_b32 m0, s7
	s_nop 0
	global_load_lds_dwordx4 v0, s[80:81]
	s_waitcnt vmcnt(8)
	s_waitcnt lgkmcnt(0)
	s_barrier
	s_setprio 1
	s_waitcnt lgkmcnt(0)
	v_mfma_f32_16x16x32_bf16 v[128:131], v[132:135], v[170:173], v[128:131]
	v_mfma_f32_16x16x32_bf16 v[124:127], v[140:143], v[170:173], v[124:127]
	v_mfma_f32_16x16x32_bf16 v[112:115], v[132:135], v[178:181], v[112:115]
	v_mfma_f32_16x16x32_bf16 v[108:111], v[140:143], v[178:181], v[108:111]
	v_mfma_f32_16x16x32_bf16 v[96:99], v[132:135], v[186:189], v[96:99]
	v_mfma_f32_16x16x32_bf16 v[92:95], v[140:143], v[186:189], v[92:95]
	v_mfma_f32_16x16x32_bf16 v[80:83], v[132:135], v[194:197], v[80:83]
	v_mfma_f32_16x16x32_bf16 v[76:79], v[140:143], v[194:197], v[76:79]
	s_setprio 0
	s_setprio 1
	v_mfma_f32_16x16x32_bf16 v[128:131], v[136:139], v[174:177], v[128:131]
	v_mfma_f32_16x16x32_bf16 v[124:127], v[144:147], v[174:177], v[124:127]
	v_mfma_f32_16x16x32_bf16 v[112:115], v[136:139], v[182:185], v[112:115]
	v_mfma_f32_16x16x32_bf16 v[108:111], v[144:147], v[182:185], v[108:111]
	v_mfma_f32_16x16x32_bf16 v[96:99], v[136:139], v[190:193], v[96:99]
	v_mfma_f32_16x16x32_bf16 v[92:95], v[144:147], v[190:193], v[92:95]
	v_mfma_f32_16x16x32_bf16 v[80:83], v[136:139], v[198:201], v[80:83]
	v_mfma_f32_16x16x32_bf16 v[76:79], v[144:147], v[198:201], v[76:79]
	s_setprio 0
	s_setprio 1
	v_mfma_f32_16x16x32_bf16 v[120:123], v[148:151], v[170:173], v[120:123]
	v_mfma_f32_16x16x32_bf16 v[116:119], v[162:165], v[170:173], v[116:119]
	v_mfma_f32_16x16x32_bf16 v[104:107], v[148:151], v[178:181], v[104:107]
	v_mfma_f32_16x16x32_bf16 v[100:103], v[162:165], v[178:181], v[100:103]
	v_mfma_f32_16x16x32_bf16 v[88:91], v[148:151], v[186:189], v[88:91]
	v_mfma_f32_16x16x32_bf16 v[84:87], v[162:165], v[186:189], v[84:87]
	v_mfma_f32_16x16x32_bf16 v[72:75], v[148:151], v[194:197], v[72:75]
	v_mfma_f32_16x16x32_bf16 v[68:71], v[162:165], v[194:197], v[68:71]
	s_setprio 0
	s_setprio 1
	v_mfma_f32_16x16x32_bf16 v[120:123], v[152:155], v[174:177], v[120:123]
	v_mfma_f32_16x16x32_bf16 v[116:119], v[166:169], v[174:177], v[116:119]
	v_mfma_f32_16x16x32_bf16 v[104:107], v[152:155], v[182:185], v[104:107]
	v_mfma_f32_16x16x32_bf16 v[100:103], v[166:169], v[182:185], v[100:103]
	v_mfma_f32_16x16x32_bf16 v[88:91], v[152:155], v[190:193], v[88:91]
	v_mfma_f32_16x16x32_bf16 v[84:87], v[166:169], v[190:193], v[84:87]
	v_mfma_f32_16x16x32_bf16 v[72:75], v[152:155], v[198:201], v[72:75]
	v_mfma_f32_16x16x32_bf16 v[68:71], v[166:169], v[198:201], v[68:71]
	s_setprio 0
	s_barrier
	s_add_u32 s80, s60, 0x80
	s_addc_u32 s81, s61, 0
	v_mov_b32_e32 v0, v157
	s_add_i32 s49, s49, s18
	ds_read_b128 v[170:173], v161 offset:49152
	ds_read_b128 v[174:177], v161 offset:50176
	ds_read_b128 v[178:181], v161 offset:51200
	ds_read_b128 v[182:185], v161 offset:52224
	ds_read_b128 v[186:189], v161 offset:53248
	ds_read_b128 v[190:193], v161 offset:54272
	ds_read_b128 v[194:197], v161 offset:55296
	ds_read_b128 v[198:201], v161 offset:56320
	s_mov_b32 m0, s49
	s_nop 0
	global_load_lds_dwordx4 v0, s[80:81]
	v_mov_b32_e32 v0, v159
	s_add_i32 m0, s49, 0x2000
	s_add_u32 s60, s60, 0x80080
	global_load_lds_dwordx4 v0, s[80:81]
	s_addc_u32 s61, s61, 0
	v_mov_b32_e32 v0, v157
	s_add_i32 s49, s51, s18
	s_mov_b32 m0, s49
	s_nop 0
	global_load_lds_dwordx4 v0, s[60:61]
	v_mov_b32_e32 v0, v159
	s_add_i32 m0, s49, 0x2000
	s_nop 0
	global_load_lds_dwordx4 v0, s[60:61]
	v_mov_b32_e32 v0, v156
	s_mov_b32 m0, s39
	s_nop 0
	global_load_lds_dwordx4 v0, s[58:59]
	v_mov_b32_e32 v0, v158
	s_mov_b32 m0, s4
	s_nop 0
	global_load_lds_dwordx4 v0, s[58:59]
	s_waitcnt vmcnt(8)
	s_waitcnt lgkmcnt(0)
	s_barrier
	s_setprio 1
	s_waitcnt lgkmcnt(0)
	v_mfma_f32_16x16x32_bf16 v[64:67], v[132:135], v[170:173], v[64:67]
	v_mfma_f32_16x16x32_bf16 v[60:63], v[140:143], v[170:173], v[60:63]
	v_mfma_f32_16x16x32_bf16 v[48:51], v[132:135], v[178:181], v[48:51]
	v_mfma_f32_16x16x32_bf16 v[44:47], v[140:143], v[178:181], v[44:47]
	v_mfma_f32_16x16x32_bf16 v[32:35], v[132:135], v[186:189], v[32:35]
	v_mfma_f32_16x16x32_bf16 v[28:31], v[140:143], v[186:189], v[28:31]
	v_mfma_f32_16x16x32_bf16 v[16:19], v[132:135], v[194:197], v[16:19]
	v_mfma_f32_16x16x32_bf16 v[12:15], v[140:143], v[194:197], v[12:15]
	s_setprio 0
	s_setprio 1
	v_mfma_f32_16x16x32_bf16 v[64:67], v[136:139], v[174:177], v[64:67]
	v_mfma_f32_16x16x32_bf16 v[60:63], v[144:147], v[174:177], v[60:63]
	v_mfma_f32_16x16x32_bf16 v[48:51], v[136:139], v[182:185], v[48:51]
	v_mfma_f32_16x16x32_bf16 v[44:47], v[144:147], v[182:185], v[44:47]
	v_mfma_f32_16x16x32_bf16 v[32:35], v[136:139], v[190:193], v[32:35]
	v_mfma_f32_16x16x32_bf16 v[28:31], v[144:147], v[190:193], v[28:31]
	v_mfma_f32_16x16x32_bf16 v[16:19], v[136:139], v[198:201], v[16:19]
	v_mfma_f32_16x16x32_bf16 v[12:15], v[144:147], v[198:201], v[12:15]
	s_setprio 0
	s_setprio 1
	v_mfma_f32_16x16x32_bf16 v[56:59], v[148:151], v[170:173], v[56:59]
	v_mfma_f32_16x16x32_bf16 v[52:55], v[162:165], v[170:173], v[52:55]
	v_mfma_f32_16x16x32_bf16 v[40:43], v[148:151], v[178:181], v[40:43]
	v_mfma_f32_16x16x32_bf16 v[36:39], v[162:165], v[178:181], v[36:39]
	v_mfma_f32_16x16x32_bf16 v[24:27], v[148:151], v[186:189], v[24:27]
	v_mfma_f32_16x16x32_bf16 v[20:23], v[162:165], v[186:189], v[20:23]
	v_mfma_f32_16x16x32_bf16 v[8:11], v[148:151], v[194:197], v[8:11]
	v_mfma_f32_16x16x32_bf16 v[4:7], v[162:165], v[194:197], v[4:7]
	s_setprio 0
	s_setprio 1
	v_mfma_f32_16x16x32_bf16 v[56:59], v[152:155], v[174:177], v[56:59]
	v_mfma_f32_16x16x32_bf16 v[52:55], v[166:169], v[174:177], v[52:55]
	v_mfma_f32_16x16x32_bf16 v[40:43], v[152:155], v[182:185], v[40:43]
	v_mfma_f32_16x16x32_bf16 v[36:39], v[166:169], v[182:185], v[36:39]
	v_mfma_f32_16x16x32_bf16 v[24:27], v[152:155], v[190:193], v[24:27]
	v_mfma_f32_16x16x32_bf16 v[20:23], v[166:169], v[190:193], v[20:23]
	v_mfma_f32_16x16x32_bf16 v[8:11], v[152:155], v[198:201], v[8:11]
	v_mfma_f32_16x16x32_bf16 v[4:7], v[166:169], v[198:201], v[4:7]
	s_setprio 0
	s_barrier
	s_add_u32 s22, s22, 0x100
	s_addc_u32 s23, s23, 0
	s_cmp_ge_i32 s13, s37
	s_mov_b32 s49, s13
	s_cbranch_scc0 .LBB0_1827
	s_and_b64 vcc, exec, s[40:41]
	s_cbranch_vccz .LBB0_1830
	s_barrier

.LBB0_2293:
	s_add_i32 s83, s52, 2
	s_add_u32 s84, s46, s50
	s_addc_u32 s85, s47, s51
	s_add_u32 s53, s84, 0x100
	s_addc_u32 s54, s85, 0
	s_add_u32 s55, s44, s50
	s_addc_u32 s56, s45, s51
	s_add_u32 s55, s55, 0x100
	s_addc_u32 s86, s56, 0
	s_cmp_eq_u32 s82, s52
	s_cselect_b32 s56, s80, s53
	s_cselect_b32 s57, s41, s54
	s_cselect_b32 s54, s81, s55
	s_cselect_b32 s55, s43, s86
	s_add_u32 s52, s56, 0x80
	s_addc_u32 s53, s57, 0
	s_add_i32 s86, 0, 0x10000
	v_add_u32_e32 v0, s86, v167
	s_add_i32 s87, 0, 0x14000
	ds_read_b128 v[132:135], v0
	ds_read_b128 v[136:139], v0 offset:1024
	ds_read_b128 v[140:143], v0 offset:2048
	ds_read_b128 v[144:147], v0 offset:3072
	v_add_u32_e32 v0, s87, v167
	ds_read_b128 v[148:151], v0
	ds_read_b128 v[152:155], v0 offset:1024
	ds_read_b128 v[156:159], v0 offset:2048
	ds_read_b128 v[160:163], v0 offset:3072
	s_add_u32 s84, s84, 0x100080
	s_addc_u32 s85, s85, 0
	v_mov_b32_e32 v0, v2
	ds_read_b128 v[170:173], v168
	ds_read_b128 v[174:177], v168 offset:1024
	ds_read_b128 v[178:181], v168 offset:2048
	ds_read_b128 v[182:185], v168 offset:3072
	ds_read_b128 v[186:189], v168 offset:4096
	ds_read_b128 v[190:193], v168 offset:5120
	ds_read_b128 v[194:197], v168 offset:6144
	ds_read_b128 v[198:201], v168 offset:7168
	s_add_i32 m0, s37, 0xc000
	s_nop 0
	global_load_lds_dwordx4 v0, s[84:85]
	v_mov_b32_e32 v0, v165
	s_add_i32 m0, s37, 0xe000
	s_nop 0
	global_load_lds_dwordx4 v0, s[84:85]
	s_waitcnt vmcnt(8)
	s_waitcnt lgkmcnt(0)
	s_barrier
	s_setprio 1
	s_waitcnt lgkmcnt(0)
	v_mfma_f32_16x16x32_bf16 v[128:131], v[132:135], v[170:173], v[128:131]
	v_mfma_f32_16x16x32_bf16 v[124:127], v[140:143], v[170:173], v[124:127]
	v_mfma_f32_16x16x32_bf16 v[112:115], v[132:135], v[178:181], v[112:115]
	v_mfma_f32_16x16x32_bf16 v[108:111], v[140:143], v[178:181], v[108:111]
	v_mfma_f32_16x16x32_bf16 v[96:99], v[132:135], v[186:189], v[96:99]
	v_mfma_f32_16x16x32_bf16 v[92:95], v[140:143], v[186:189], v[92:95]
	v_mfma_f32_16x16x32_bf16 v[88:91], v[132:135], v[194:197], v[88:91]
	v_mfma_f32_16x16x32_bf16 v[80:83], v[140:143], v[194:197], v[80:83]
	s_setprio 0
	s_setprio 1
	v_mfma_f32_16x16x32_bf16 v[128:131], v[136:139], v[174:177], v[128:131]
	v_mfma_f32_16x16x32_bf16 v[124:127], v[144:147], v[174:177], v[124:127]
	v_mfma_f32_16x16x32_bf16 v[112:115], v[136:139], v[182:185], v[112:115]
	v_mfma_f32_16x16x32_bf16 v[108:111], v[144:147], v[182:185], v[108:111]
	v_mfma_f32_16x16x32_bf16 v[96:99], v[136:139], v[190:193], v[96:99]
	v_mfma_f32_16x16x32_bf16 v[92:95], v[144:147], v[190:193], v[92:95]
	v_mfma_f32_16x16x32_bf16 v[88:91], v[136:139], v[198:201], v[88:91]
	v_mfma_f32_16x16x32_bf16 v[80:83], v[144:147], v[198:201], v[80:83]
	s_setprio 0
	s_setprio 1
	v_mfma_f32_16x16x32_bf16 v[120:123], v[148:151], v[170:173], v[120:123]
	v_mfma_f32_16x16x32_bf16 v[116:119], v[156:159], v[170:173], v[116:119]
	v_mfma_f32_16x16x32_bf16 v[104:107], v[148:151], v[178:181], v[104:107]
	v_mfma_f32_16x16x32_bf16 v[100:103], v[156:159], v[178:181], v[100:103]
	v_mfma_f32_16x16x32_bf16 v[84:87], v[148:151], v[186:189], v[84:87]
	v_mfma_f32_16x16x32_bf16 v[76:79], v[156:159], v[186:189], v[76:79]
	v_mfma_f32_16x16x32_bf16 v[72:75], v[148:151], v[194:197], v[72:75]
	v_mfma_f32_16x16x32_bf16 v[68:71], v[156:159], v[194:197], v[68:71]
	s_setprio 0
	s_setprio 1
	v_mfma_f32_16x16x32_bf16 v[120:123], v[152:155], v[174:177], v[120:123]
	v_mfma_f32_16x16x32_bf16 v[116:119], v[160:163], v[174:177], v[116:119]
	v_mfma_f32_16x16x32_bf16 v[104:107], v[152:155], v[182:185], v[104:107]
	v_mfma_f32_16x16x32_bf16 v[100:103], v[160:163], v[182:185], v[100:103]
	v_mfma_f32_16x16x32_bf16 v[84:87], v[152:155], v[190:193], v[84:87]
	v_mfma_f32_16x16x32_bf16 v[76:79], v[160:163], v[190:193], v[76:79]
	v_mfma_f32_16x16x32_bf16 v[72:75], v[152:155], v[198:201], v[72:75]
	v_mfma_f32_16x16x32_bf16 v[68:71], v[160:163], v[198:201], v[68:71]
	s_setprio 0
	s_barrier
	s_mov_b64 s[84:85], s[54:55]
	v_mov_b32_e32 v0, v164
	s_add_i32 s86, s86, s39
	ds_read_b128 v[170:173], v168 offset:16384
	ds_read_b128 v[174:177], v168 offset:17408
	ds_read_b128 v[178:181], v168 offset:18432
	ds_read_b128 v[182:185], v168 offset:19456
	ds_read_b128 v[186:189], v168 offset:20480
	ds_read_b128 v[190:193], v168 offset:21504
	ds_read_b128 v[194:197], v168 offset:22528
	ds_read_b128 v[198:201], v168 offset:23552
	s_mov_b32 m0, s86
	s_nop 0
	global_load_lds_dwordx4 v0, s[84:85]
	v_mov_b32_e32 v0, v166
	s_add_i32 m0, s86, 0x2000
	s_nop 0
	global_load_lds_dwordx4 v0, s[84:85]
	s_add_u32 s84, s54, 0x100000
	s_addc_u32 s85, s55, 0
	v_mov_b32_e32 v0, v164
	s_add_i32 s86, s87, s39
	s_mov_b32 m0, s86
	s_nop 0
	global_load_lds_dwordx4 v0, s[84:85]
	v_mov_b32_e32 v0, v166
	s_add_i32 m0, s86, 0x2000
	s_nop 0
	global_load_lds_dwordx4 v0, s[84:85]
	s_mov_b64 s[84:85], s[56:57]
	v_mov_b32_e32 v0, v2
	s_mov_b32 m0, s37
	s_nop 0
	global_load_lds_dwordx4 v0, s[84:85]
	v_mov_b32_e32 v0, v165
	s_mov_b32 m0, s8
	s_nop 0
	global_load_lds_dwordx4 v0, s[84:85]
	s_waitcnt vmcnt(8)
	s_waitcnt lgkmcnt(0)
	s_barrier
	s_setprio 1
	s_waitcnt lgkmcnt(0)
	v_mfma_f32_16x16x32_bf16 v[64:67], v[132:135], v[170:173], v[64:67]
	v_mfma_f32_16x16x32_bf16 v[60:63], v[140:143], v[170:173], v[60:63]
	v_mfma_f32_16x16x32_bf16 v[56:59], v[132:135], v[178:181], v[56:59]
	v_mfma_f32_16x16x32_bf16 v[48:51], v[140:143], v[178:181], v[48:51]
	v_mfma_f32_16x16x32_bf16 v[40:43], v[132:135], v[186:189], v[40:43]
	v_mfma_f32_16x16x32_bf16 v[32:35], v[140:143], v[186:189], v[32:35]
	v_mfma_f32_16x16x32_bf16 v[24:27], v[132:135], v[194:197], v[24:27]
	v_mfma_f32_16x16x32_bf16 v[16:19], v[140:143], v[194:197], v[16:19]
	s_setprio 0
	s_setprio 1
	v_mfma_f32_16x16x32_bf16 v[64:67], v[136:139], v[174:177], v[64:67]
	v_mfma_f32_16x16x32_bf16 v[60:63], v[144:147], v[174:177], v[60:63]
	v_mfma_f32_16x16x32_bf16 v[56:59], v[136:139], v[182:185], v[56:59]
	v_mfma_f32_16x16x32_bf16 v[48:51], v[144:147], v[182:185], v[48:51]
	v_mfma_f32_16x16x32_bf16 v[40:43], v[136:139], v[190:193], v[40:43]
	v_mfma_f32_16x16x32_bf16 v[32:35], v[144:147], v[190:193], v[32:35]
	v_mfma_f32_16x16x32_bf16 v[24:27], v[136:139], v[198:201], v[24:27]
	v_mfma_f32_16x16x32_bf16 v[16:19], v[144:147], v[198:201], v[16:19]
	s_setprio 0
	s_setprio 1
	v_mfma_f32_16x16x32_bf16 v[52:55], v[148:151], v[170:173], v[52:55]
	v_mfma_f32_16x16x32_bf16 v[44:47], v[156:159], v[170:173], v[44:47]
	v_mfma_f32_16x16x32_bf16 v[36:39], v[148:151], v[178:181], v[36:39]
	v_mfma_f32_16x16x32_bf16 v[28:31], v[156:159], v[178:181], v[28:31]
	v_mfma_f32_16x16x32_bf16 v[20:23], v[148:151], v[186:189], v[20:23]
	v_mfma_f32_16x16x32_bf16 v[12:15], v[156:159], v[186:189], v[12:15]
	v_mfma_f32_16x16x32_bf16 v[8:11], v[148:151], v[194:197], v[8:11]
	v_mfma_f32_16x16x32_bf16 v[4:7], v[156:159], v[194:197], v[4:7]
	s_setprio 0
	s_setprio 1
	v_mfma_f32_16x16x32_bf16 v[52:55], v[152:155], v[174:177], v[52:55]
	v_mfma_f32_16x16x32_bf16 v[44:47], v[160:163], v[174:177], v[44:47]
	v_mfma_f32_16x16x32_bf16 v[36:39], v[152:155], v[182:185], v[36:39]
	v_mfma_f32_16x16x32_bf16 v[28:31], v[160:163], v[182:185], v[28:31]
	v_mfma_f32_16x16x32_bf16 v[20:23], v[152:155], v[190:193], v[20:23]
	v_mfma_f32_16x16x32_bf16 v[12:15], v[160:163], v[190:193], v[12:15]
	v_mfma_f32_16x16x32_bf16 v[8:11], v[152:155], v[198:201], v[8:11]
	v_mfma_f32_16x16x32_bf16 v[4:7], v[160:163], v[198:201], v[4:7]
	s_setprio 0
	s_barrier
	s_add_i32 s84, 0, 0x18000
	v_add_u32_e32 v0, s84, v167
	s_add_i32 s85, 0, 0x1c000
	ds_read_b128 v[132:135], v0
	ds_read_b128 v[136:139], v0 offset:1024
	ds_read_b128 v[140:143], v0 offset:2048
	ds_read_b128 v[144:147], v0 offset:3072
	v_add_u32_e32 v0, s85, v167
	ds_read_b128 v[148:151], v0
	ds_read_b128 v[152:155], v0 offset:1024
	ds_read_b128 v[156:159], v0 offset:2048
	ds_read_b128 v[160:163], v0 offset:3072
	s_add_u32 s56, s56, 0x100000
	s_addc_u32 s57, s57, 0
	v_mov_b32_e32 v0, v2
	s_mov_b32 m0, s9
	ds_read_b128 v[170:173], v168 offset:32768
	ds_read_b128 v[174:177], v168 offset:33792
	ds_read_b128 v[178:181], v168 offset:34816
	ds_read_b128 v[182:185], v168 offset:35840
	ds_read_b128 v[186:189], v168 offset:36864
	ds_read_b128 v[190:193], v168 offset:37888
	ds_read_b128 v[194:197], v168 offset:38912
	ds_read_b128 v[198:201], v168 offset:39936
	s_nop 0
	global_load_lds_dwordx4 v0, s[56:57]
	v_mov_b32_e32 v0, v165
	s_mov_b32 m0, s35
	s_nop 0
	global_load_lds_dwordx4 v0, s[56:57]
	s_waitcnt vmcnt(8)
	s_waitcnt lgkmcnt(0)
	s_barrier
	s_setprio 1
	s_waitcnt lgkmcnt(0)
	v_mfma_f32_16x16x32_bf16 v[128:131], v[132:135], v[170:173], v[128:131]
	v_mfma_f32_16x16x32_bf16 v[124:127], v[140:143], v[170:173], v[124:127]
	v_mfma_f32_16x16x32_bf16 v[112:115], v[132:135], v[178:181], v[112:115]
	v_mfma_f32_16x16x32_bf16 v[108:111], v[140:143], v[178:181], v[108:111]
	v_mfma_f32_16x16x32_bf16 v[96:99], v[132:135], v[186:189], v[96:99]
	v_mfma_f32_16x16x32_bf16 v[92:95], v[140:143], v[186:189], v[92:95]
	v_mfma_f32_16x16x32_bf16 v[88:91], v[132:135], v[194:197], v[88:91]
	v_mfma_f32_16x16x32_bf16 v[80:83], v[140:143], v[194:197], v[80:83]
	s_setprio 0
	s_setprio 1
	v_mfma_f32_16x16x32_bf16 v[128:131], v[136:139], v[174:177], v[128:131]
	v_mfma_f32_16x16x32_bf16 v[124:127], v[144:147], v[174:177], v[124:127]
	v_mfma_f32_16x16x32_bf16 v[112:115], v[136:139], v[182:185], v[112:115]
	v_mfma_f32_16x16x32_bf16 v[108:111], v[144:147], v[182:185], v[108:111]
	v_mfma_f32_16x16x32_bf16 v[96:99], v[136:139], v[190:193], v[96:99]
	v_mfma_f32_16x16x32_bf16 v[92:95], v[144:147], v[190:193], v[92:95]
	v_mfma_f32_16x16x32_bf16 v[88:91], v[136:139], v[198:201], v[88:91]
	v_mfma_f32_16x16x32_bf16 v[80:83], v[144:147], v[198:201], v[80:83]
	s_setprio 0
	s_setprio 1
	v_mfma_f32_16x16x32_bf16 v[120:123], v[148:151], v[170:173], v[120:123]
	v_mfma_f32_16x16x32_bf16 v[116:119], v[156:159], v[170:173], v[116:119]
	v_mfma_f32_16x16x32_bf16 v[104:107], v[148:151], v[178:181], v[104:107]
	v_mfma_f32_16x16x32_bf16 v[100:103], v[156:159], v[178:181], v[100:103]
	v_mfma_f32_16x16x32_bf16 v[84:87], v[148:151], v[186:189], v[84:87]
	v_mfma_f32_16x16x32_bf16 v[76:79], v[156:159], v[186:189], v[76:79]
	v_mfma_f32_16x16x32_bf16 v[72:75], v[148:151], v[194:197], v[72:75]
	v_mfma_f32_16x16x32_bf16 v[68:71], v[156:159], v[194:197], v[68:71]
	s_setprio 0
	s_setprio 1
	v_mfma_f32_16x16x32_bf16 v[120:123], v[152:155], v[174:177], v[120:123]
	v_mfma_f32_16x16x32_bf16 v[116:119], v[160:163], v[174:177], v[116:119]
	v_mfma_f32_16x16x32_bf16 v[104:107], v[152:155], v[182:185], v[104:107]
	v_mfma_f32_16x16x32_bf16 v[100:103], v[160:163], v[182:185], v[100:103]
	v_mfma_f32_16x16x32_bf16 v[84:87], v[152:155], v[190:193], v[84:87]
	v_mfma_f32_16x16x32_bf16 v[76:79], v[160:163], v[190:193], v[76:79]
	v_mfma_f32_16x16x32_bf16 v[72:75], v[152:155], v[198:201], v[72:75]
	v_mfma_f32_16x16x32_bf16 v[68:71], v[160:163], v[198:201], v[68:71]
	s_setprio 0
	s_barrier
	s_add_u32 s56, s54, 0x80
	s_addc_u32 s57, s55, 0
	v_mov_b32_e32 v0, v164
	s_add_i32 s84, s84, s39
	ds_read_b128 v[170:173], v168 offset:49152
	ds_read_b128 v[174:177], v168 offset:50176
	ds_read_b128 v[178:181], v168 offset:51200
	ds_read_b128 v[182:185], v168 offset:52224
	ds_read_b128 v[186:189], v168 offset:53248
	ds_read_b128 v[190:193], v168 offset:54272
	ds_read_b128 v[194:197], v168 offset:55296
	ds_read_b128 v[198:201], v168 offset:56320
	s_mov_b32 m0, s84
	s_nop 0
	global_load_lds_dwordx4 v0, s[56:57]
	v_mov_b32_e32 v0, v166
	s_add_i32 m0, s84, 0x2000
	s_add_u32 s54, s54, 0x100080
	global_load_lds_dwordx4 v0, s[56:57]
	s_addc_u32 s55, s55, 0
	v_mov_b32_e32 v0, v164
	s_add_i32 s56, s85, s39
	s_mov_b32 m0, s56
	s_nop 0
	global_load_lds_dwordx4 v0, s[54:55]
	v_mov_b32_e32 v0, v166
	s_add_i32 m0, s56, 0x2000
	s_nop 0
	global_load_lds_dwordx4 v0, s[54:55]
	v_mov_b32_e32 v0, v2
	s_mov_b32 m0, s58
	s_nop 0
	global_load_lds_dwordx4 v0, s[52:53]
	v_mov_b32_e32 v0, v165
	s_mov_b32 m0, s59
	s_nop 0
	global_load_lds_dwordx4 v0, s[52:53]
	s_waitcnt vmcnt(8)
	s_waitcnt lgkmcnt(0)
	s_barrier
	s_setprio 1
	s_waitcnt lgkmcnt(0)
	v_mfma_f32_16x16x32_bf16 v[64:67], v[132:135], v[170:173], v[64:67]
	v_mfma_f32_16x16x32_bf16 v[60:63], v[140:143], v[170:173], v[60:63]
	v_mfma_f32_16x16x32_bf16 v[56:59], v[132:135], v[178:181], v[56:59]
	v_mfma_f32_16x16x32_bf16 v[48:51], v[140:143], v[178:181], v[48:51]
	v_mfma_f32_16x16x32_bf16 v[40:43], v[132:135], v[186:189], v[40:43]
	v_mfma_f32_16x16x32_bf16 v[32:35], v[140:143], v[186:189], v[32:35]
	v_mfma_f32_16x16x32_bf16 v[24:27], v[132:135], v[194:197], v[24:27]
	v_mfma_f32_16x16x32_bf16 v[16:19], v[140:143], v[194:197], v[16:19]
	s_setprio 0
	s_setprio 1
	v_mfma_f32_16x16x32_bf16 v[64:67], v[136:139], v[174:177], v[64:67]
	v_mfma_f32_16x16x32_bf16 v[60:63], v[144:147], v[174:177], v[60:63]
	v_mfma_f32_16x16x32_bf16 v[56:59], v[136:139], v[182:185], v[56:59]
	v_mfma_f32_16x16x32_bf16 v[48:51], v[144:147], v[182:185], v[48:51]
	v_mfma_f32_16x16x32_bf16 v[40:43], v[136:139], v[190:193], v[40:43]
	v_mfma_f32_16x16x32_bf16 v[32:35], v[144:147], v[190:193], v[32:35]
	v_mfma_f32_16x16x32_bf16 v[24:27], v[136:139], v[198:201], v[24:27]
	v_mfma_f32_16x16x32_bf16 v[16:19], v[144:147], v[198:201], v[16:19]
	s_setprio 0
	s_setprio 1
	v_mfma_f32_16x16x32_bf16 v[52:55], v[148:151], v[170:173], v[52:55]
	v_mfma_f32_16x16x32_bf16 v[44:47], v[156:159], v[170:173], v[44:47]
	v_mfma_f32_16x16x32_bf16 v[36:39], v[148:151], v[178:181], v[36:39]
	v_mfma_f32_16x16x32_bf16 v[28:31], v[156:159], v[178:181], v[28:31]
	v_mfma_f32_16x16x32_bf16 v[20:23], v[148:151], v[186:189], v[20:23]
	v_mfma_f32_16x16x32_bf16 v[12:15], v[156:159], v[186:189], v[12:15]
	v_mfma_f32_16x16x32_bf16 v[8:11], v[148:151], v[194:197], v[8:11]
	v_mfma_f32_16x16x32_bf16 v[4:7], v[156:159], v[194:197], v[4:7]
	s_setprio 0
	s_setprio 1
	v_mfma_f32_16x16x32_bf16 v[52:55], v[152:155], v[174:177], v[52:55]
	v_mfma_f32_16x16x32_bf16 v[44:47], v[160:163], v[174:177], v[44:47]
	v_mfma_f32_16x16x32_bf16 v[36:39], v[152:155], v[182:185], v[36:39]
	v_mfma_f32_16x16x32_bf16 v[28:31], v[160:163], v[182:185], v[28:31]
	v_mfma_f32_16x16x32_bf16 v[20:23], v[152:155], v[190:193], v[20:23]
	v_mfma_f32_16x16x32_bf16 v[12:15], v[160:163], v[190:193], v[12:15]
	v_mfma_f32_16x16x32_bf16 v[8:11], v[152:155], v[198:201], v[8:11]
	v_mfma_f32_16x16x32_bf16 v[4:7], v[160:163], v[198:201], v[4:7]
	s_setprio 0
	s_barrier
	s_add_u32 s50, s50, 0x100
	s_addc_u32 s51, s51, 0
	s_cmp_ge_i32 s83, s4
	s_mov_b32 s52, s83
	s_cbranch_scc0 .LBB0_2293
	s_and_b64 vcc, exec, s[20:21]
	s_cbranch_vccz .LBB0_2296
	s_barrier
